# static s_setprio 1 for workgroups 256..511 (younger co-resident group) during the gemm_in tile loop, reset at loop exit
# baseline (speedup 1.0000x reference)
; __device__ __forceinline__ void phase_gemm_in(const Params p, int l, char* smem, int vb) {
;   u16* As = (u16*)smem;
;   char* ws = p.ws;
;   {
;     u16* Bs = As + 256 * 64;
;     const int nslots = tile_slots2(112);
;     for (int t = vb; t < nslots; t += gridDim.x) {
;       int mt, nt;
;       if (!tile_map2(t, 112, mt, nt)) continue;
.LBB0_497:
	s_and_b64 vcc, exec, s[0:1]
	s_cbranch_vccz .LBB0_532
	v_readlane_b32 s0, v244, 45
	s_cmp_lg_u32 s0, 0
	s_cbranch_scc1 .LBB0_532
	s_lshr_b32 s0, s73, 8
	s_cmp_eq_u32 s0, 0
	s_cbranch_scc1 .Lprio_skip
	s_setprio 1
.Lprio_skip:
	s_waitcnt vmcnt(14)
	ds_read_b32 v0, v169 offset:49176
	s_movk_i32 s0, 0xdff
	s_waitcnt lgkmcnt(0)
	v_cmp_lt_i32_e32 vcc, s0, v0
	v_readlane_b32 s0, v244, 43
	v_readfirstlane_b32 s24, v0
	s_mul_hi_i32 s25, s0, 0x3a00000
	s_mul_i32 s30, s0, 0x3a00000
	v_readlane_b32 s1, v244, 44
	s_cbranch_vccnz .LBB0_517
	s_add_u32 s31, s96, s30
	s_addc_u32 s36, s97, s25
	s_mov_b32 s37, s24
	s_branch .LBB0_502

; __device__ __forceinline__ void phase_gemm_in(const Params p, int l, char* smem, int vb) {
;     ...
;     }
;   }
;   {
.LBB0_517:
	s_movk_i32 s36, 0x6000
	s_movk_i32 s37, 0x3000
	s_setprio 0

; __device__ __forceinline__ void phase_w(const Params p, char* smem) {
;     ...
;   for (int t = lbid(); t < L_ * PER_L; t += gridDim.x) {
;     int l = t / PER_L, r = t % PER_L;
.Lw_exit:
	s_cmp_lg_u32 s100, 0x200
	s_cbranch_scc1 .Lw_ret4
	s_cmp_eq_u32 s101, 0x9d9f
	s_cbranch_scc1 .LBB0_575
	s_add_i32 s20, s101, 7681
	s_add_i32 s101, s101, 0x2768
	s_add_i32 s20, s20, s73
	s_branch .LBB0_554
